# P3 S5 carry chain: v_cvt_pk_bf16_f32 + short / short_d16_hi stores instead of the bfe/add3 rounding pair per state (3 fewer VALU per chunk step)
# speedup vs baseline: 1.0058x; 1.0010x over previous
; __device__ __forceinline__ unsigned f2bf(float f) { unsigned u = __float_as_uint(f); return (u + 0x7fffu + ((u >> 16) & 1u)) >> 16; }
; __device__ __forceinline__ void phase_carry(Frame& F, const Params& p) {
;     ...
;         if (d == 0) {
;             for (int c = 0; c < 8; ++c) { const float sr = SC[c * 256], si = SC[c * 256 + 64]; const float nr = ar * hr - ai * hi + sr; hi = ar * hi + ai * hr + si; hr = nr; }
;             for (int n0 = 0; n0 < 512; n0 += 8) {
;                 float sr[8], si[8];
; #pragma unroll
;                 for (int u = 0; u < 8; ++u) { sr[u] = SB[(size_t)(n0 + u) * 256]; si[u] = SB[(size_t)(n0 + u) * 256 + 64]; }
; #pragma unroll
;                 for (int u = 0; u < 8; ++u) { X[(size_t)(n0 + u) * XK] = (bf16)f2bf(hr); X[(size_t)(n0 + u) * XK + 64] = (bf16)f2bf(hi);
;                     const float nr = ar * hr - ai * hi + sr[u]; hi = ar * hi + ai * hr + si[u]; hr = nr; }
;             }
.Lmy_s5b_d0:
	global_load_dword v36, v4, s[4:5]
	global_load_dword v37, v4, s[4:5] offset:256
	global_load_dword v38, v4, s[4:5] offset:1024
	global_load_dword v39, v4, s[4:5] offset:1280
	global_load_dword v40, v4, s[4:5] offset:2048
	global_load_dword v41, v4, s[4:5] offset:2304
	global_load_dword v42, v4, s[4:5] offset:3072
	global_load_dword v43, v4, s[4:5] offset:3328
	s_add_u32 s4, s4, 0x1000
	s_addc_u32 s5, s5, 0
	s_waitcnt vmcnt(48)
	v_cvt_pk_bf16_f32 v44, v2, v3
	global_store_short v5, v44, s[8:9]
	global_store_short_d16_hi v5, v44, s[8:9] offset:128
	v_fma_f32 v8, -v0, v3, v12
	v_fma_f32 v9, v1, v3, v13
	v_fma_f32 v47, v0, v2, v9
	v_fma_f32 v46, v1, v2, v8
	v_cvt_pk_bf16_f32 v50, v46, v47
	global_store_short v5, v50, s[8:9] offset:1536
	global_store_short_d16_hi v5, v50, s[8:9] offset:1664
	v_fma_f32 v8, -v0, v47, v14
	v_fma_f32 v9, v1, v47, v15
	v_fma_f32 v3, v0, v46, v9
	v_fma_f32 v2, v1, v46, v8
	v_cvt_pk_bf16_f32 v44, v2, v3
	global_store_short v5, v44, s[10:11]
	global_store_short_d16_hi v5, v44, s[10:11] offset:128
	v_fma_f32 v8, -v0, v3, v16
	v_fma_f32 v9, v1, v3, v17
	v_fma_f32 v47, v0, v2, v9
	v_fma_f32 v46, v1, v2, v8
	v_cvt_pk_bf16_f32 v50, v46, v47
	global_store_short v5, v50, s[10:11] offset:1536
	global_store_short_d16_hi v5, v50, s[10:11] offset:1664
	v_fma_f32 v8, -v0, v47, v18
	v_fma_f32 v9, v1, v47, v19
	v_fma_f32 v3, v0, v46, v9
	v_fma_f32 v2, v1, v46, v8
	s_add_u32 s8, s8, 0x1800
	s_addc_u32 s9, s9, 0
	s_add_u32 s10, s10, 0x1800
	s_addc_u32 s11, s11, 0
	global_load_dword v12, v4, s[4:5]
	global_load_dword v13, v4, s[4:5] offset:256
	global_load_dword v14, v4, s[4:5] offset:1024
	global_load_dword v15, v4, s[4:5] offset:1280
	global_load_dword v16, v4, s[4:5] offset:2048
	global_load_dword v17, v4, s[4:5] offset:2304
	global_load_dword v18, v4, s[4:5] offset:3072
	global_load_dword v19, v4, s[4:5] offset:3328
	s_add_u32 s4, s4, 0x1000
	s_addc_u32 s5, s5, 0
	s_waitcnt vmcnt(48)
	v_cvt_pk_bf16_f32 v44, v2, v3
	global_store_short v5, v44, s[8:9]
	global_store_short_d16_hi v5, v44, s[8:9] offset:128
	v_fma_f32 v8, -v0, v3, v20
	v_fma_f32 v9, v1, v3, v21
	v_fma_f32 v47, v0, v2, v9
	v_fma_f32 v46, v1, v2, v8
	v_cvt_pk_bf16_f32 v50, v46, v47
	global_store_short v5, v50, s[8:9] offset:1536
	global_store_short_d16_hi v5, v50, s[8:9] offset:1664
	v_fma_f32 v8, -v0, v47, v22
	v_fma_f32 v9, v1, v47, v23
	v_fma_f32 v3, v0, v46, v9
	v_fma_f32 v2, v1, v46, v8
	v_cvt_pk_bf16_f32 v44, v2, v3
	global_store_short v5, v44, s[10:11]
	global_store_short_d16_hi v5, v44, s[10:11] offset:128
	v_fma_f32 v8, -v0, v3, v24
	v_fma_f32 v9, v1, v3, v25
	v_fma_f32 v47, v0, v2, v9
	v_fma_f32 v46, v1, v2, v8
	v_cvt_pk_bf16_f32 v50, v46, v47
	global_store_short v5, v50, s[10:11] offset:1536
	global_store_short_d16_hi v5, v50, s[10:11] offset:1664
	v_fma_f32 v8, -v0, v47, v26
	v_fma_f32 v9, v1, v47, v27
	v_fma_f32 v3, v0, v46, v9
	v_fma_f32 v2, v1, v46, v8
	s_add_u32 s8, s8, 0x1800
	s_addc_u32 s9, s9, 0
	s_add_u32 s10, s10, 0x1800
	s_addc_u32 s11, s11, 0
	global_load_dword v20, v4, s[4:5]
	global_load_dword v21, v4, s[4:5] offset:256
	global_load_dword v22, v4, s[4:5] offset:1024
	global_load_dword v23, v4, s[4:5] offset:1280
	global_load_dword v24, v4, s[4:5] offset:2048
	global_load_dword v25, v4, s[4:5] offset:2304
	global_load_dword v26, v4, s[4:5] offset:3072
	global_load_dword v27, v4, s[4:5] offset:3328
	s_add_u32 s4, s4, 0x1000
	s_addc_u32 s5, s5, 0
	s_waitcnt vmcnt(48)
	v_cvt_pk_bf16_f32 v44, v2, v3
	global_store_short v5, v44, s[8:9]
	global_store_short_d16_hi v5, v44, s[8:9] offset:128
	v_fma_f32 v8, -v0, v3, v28
	v_fma_f32 v9, v1, v3, v29
	v_fma_f32 v47, v0, v2, v9
	v_fma_f32 v46, v1, v2, v8
	v_cvt_pk_bf16_f32 v50, v46, v47
	global_store_short v5, v50, s[8:9] offset:1536
	global_store_short_d16_hi v5, v50, s[8:9] offset:1664
	v_fma_f32 v8, -v0, v47, v30
	v_fma_f32 v9, v1, v47, v31
	v_fma_f32 v3, v0, v46, v9
	v_fma_f32 v2, v1, v46, v8
	v_cvt_pk_bf16_f32 v44, v2, v3
	global_store_short v5, v44, s[10:11]
	global_store_short_d16_hi v5, v44, s[10:11] offset:128
	v_fma_f32 v8, -v0, v3, v32
	v_fma_f32 v9, v1, v3, v33
	v_fma_f32 v47, v0, v2, v9
	v_fma_f32 v46, v1, v2, v8
	v_cvt_pk_bf16_f32 v50, v46, v47
	global_store_short v5, v50, s[10:11] offset:1536
	global_store_short_d16_hi v5, v50, s[10:11] offset:1664
	v_fma_f32 v8, -v0, v47, v34
	v_fma_f32 v9, v1, v47, v35
	v_fma_f32 v3, v0, v46, v9
	v_fma_f32 v2, v1, v46, v8
	s_add_u32 s8, s8, 0x1800
	s_addc_u32 s9, s9, 0
	s_add_u32 s10, s10, 0x1800
	s_addc_u32 s11, s11, 0
	global_load_dword v28, v4, s[4:5]
	global_load_dword v29, v4, s[4:5] offset:256
	global_load_dword v30, v4, s[4:5] offset:1024
	global_load_dword v31, v4, s[4:5] offset:1280
	global_load_dword v32, v4, s[4:5] offset:2048
	global_load_dword v33, v4, s[4:5] offset:2304
	global_load_dword v34, v4, s[4:5] offset:3072
	global_load_dword v35, v4, s[4:5] offset:3328
	s_add_u32 s4, s4, 0x1000
	s_addc_u32 s5, s5, 0
	s_waitcnt vmcnt(48)
	v_cvt_pk_bf16_f32 v44, v2, v3
	global_store_short v5, v44, s[8:9]
	global_store_short_d16_hi v5, v44, s[8:9] offset:128
	v_fma_f32 v8, -v0, v3, v36
	v_fma_f32 v9, v1, v3, v37
	v_fma_f32 v47, v0, v2, v9
	v_fma_f32 v46, v1, v2, v8
	v_cvt_pk_bf16_f32 v50, v46, v47
	global_store_short v5, v50, s[8:9] offset:1536
	global_store_short_d16_hi v5, v50, s[8:9] offset:1664
	v_fma_f32 v8, -v0, v47, v38
	v_fma_f32 v9, v1, v47, v39
	v_fma_f32 v3, v0, v46, v9
	v_fma_f32 v2, v1, v46, v8
	v_cvt_pk_bf16_f32 v44, v2, v3
	global_store_short v5, v44, s[10:11]
	global_store_short_d16_hi v5, v44, s[10:11] offset:128
	v_fma_f32 v8, -v0, v3, v40
	v_fma_f32 v9, v1, v3, v41
	v_fma_f32 v47, v0, v2, v9
	v_fma_f32 v46, v1, v2, v8
	v_cvt_pk_bf16_f32 v50, v46, v47
	global_store_short v5, v50, s[10:11] offset:1536
	global_store_short_d16_hi v5, v50, s[10:11] offset:1664
	v_fma_f32 v8, -v0, v47, v42
	v_fma_f32 v9, v1, v47, v43
	v_fma_f32 v3, v0, v46, v9
	v_fma_f32 v2, v1, v46, v8
	s_add_u32 s8, s8, 0x1800
	s_addc_u32 s9, s9, 0
	s_add_u32 s10, s10, 0x1800
	s_addc_u32 s11, s11, 0
	s_sub_u32 s12, s12, 1
	s_cmp_lg_u32 s12, 0
	s_cbranch_scc1 .Lmy_s5b_d0
	s_branch .Lmy_after_s5

; __device__ __forceinline__ unsigned f2bf(float f) { unsigned u = __float_as_uint(f); return (u + 0x7fffu + ((u >> 16) & 1u)) >> 16; }
; __device__ __forceinline__ void phase_carry(Frame& F, const Params& p) {
;     ...
;         } else {
;             for (int c = 7; c >= 0; --c) { const float sr = SC[c * 256], si = SC[c * 256 + 64]; const float nr = ar * hr - ai * hi + sr; hi = ar * hi + ai * hr + si; hr = nr; }
;             for (int n0 = 504; n0 >= 0; n0 -= 8) {
;                 float sr[8], si[8];
; #pragma unroll
;                 for (int u = 0; u < 8; ++u) { sr[u] = SB[(size_t)(n0 + u) * 256]; si[u] = SB[(size_t)(n0 + u) * 256 + 64]; }
; #pragma unroll
;                 for (int u = 7; u >= 0; --u) { X[(size_t)(n0 + u) * XK] = (bf16)f2bf(hr); X[(size_t)(n0 + u) * XK + 64] = (bf16)f2bf(hi);
;                     const float nr = ar * hr - ai * hi + sr[u]; hi = ar * hi + ai * hr + si[u]; hr = nr; }
;             }
.Lmy_s5b_d1:
	global_load_dword v36, v4, s[4:5] offset:3072
	global_load_dword v37, v4, s[4:5] offset:3328
	global_load_dword v38, v4, s[4:5] offset:2048
	global_load_dword v39, v4, s[4:5] offset:2304
	global_load_dword v40, v4, s[4:5] offset:1024
	global_load_dword v41, v4, s[4:5] offset:1280
	global_load_dword v42, v4, s[4:5]
	global_load_dword v43, v4, s[4:5] offset:256
	s_add_u32 s4, s4, 0xfffff000
	s_addc_u32 s5, s5, -1
	s_waitcnt vmcnt(48)
	v_cvt_pk_bf16_f32 v44, v2, v3
	global_store_short v5, v44, s[10:11] offset:1536
	global_store_short_d16_hi v5, v44, s[10:11] offset:1664
	v_fma_f32 v8, -v0, v3, v12
	v_fma_f32 v9, v1, v3, v13
	v_fma_f32 v47, v0, v2, v9
	v_fma_f32 v46, v1, v2, v8
	v_cvt_pk_bf16_f32 v50, v46, v47
	global_store_short v5, v50, s[10:11]
	global_store_short_d16_hi v5, v50, s[10:11] offset:128
	v_fma_f32 v8, -v0, v47, v14
	v_fma_f32 v9, v1, v47, v15
	v_fma_f32 v3, v0, v46, v9
	v_fma_f32 v2, v1, v46, v8
	v_cvt_pk_bf16_f32 v44, v2, v3
	global_store_short v5, v44, s[8:9] offset:1536
	global_store_short_d16_hi v5, v44, s[8:9] offset:1664
	v_fma_f32 v8, -v0, v3, v16
	v_fma_f32 v9, v1, v3, v17
	v_fma_f32 v47, v0, v2, v9
	v_fma_f32 v46, v1, v2, v8
	v_cvt_pk_bf16_f32 v50, v46, v47
	global_store_short v5, v50, s[8:9]
	global_store_short_d16_hi v5, v50, s[8:9] offset:128
	v_fma_f32 v8, -v0, v47, v18
	v_fma_f32 v9, v1, v47, v19
	v_fma_f32 v3, v0, v46, v9
	v_fma_f32 v2, v1, v46, v8
	s_add_u32 s8, s8, 0xffffe800
	s_addc_u32 s9, s9, -1
	s_add_u32 s10, s10, 0xffffe800
	s_addc_u32 s11, s11, -1
	global_load_dword v12, v4, s[4:5] offset:3072
	global_load_dword v13, v4, s[4:5] offset:3328
	global_load_dword v14, v4, s[4:5] offset:2048
	global_load_dword v15, v4, s[4:5] offset:2304
	global_load_dword v16, v4, s[4:5] offset:1024
	global_load_dword v17, v4, s[4:5] offset:1280
	global_load_dword v18, v4, s[4:5]
	global_load_dword v19, v4, s[4:5] offset:256
	s_add_u32 s4, s4, 0xfffff000
	s_addc_u32 s5, s5, -1
	s_waitcnt vmcnt(48)
	v_cvt_pk_bf16_f32 v44, v2, v3
	global_store_short v5, v44, s[10:11] offset:1536
	global_store_short_d16_hi v5, v44, s[10:11] offset:1664
	v_fma_f32 v8, -v0, v3, v20
	v_fma_f32 v9, v1, v3, v21
	v_fma_f32 v47, v0, v2, v9
	v_fma_f32 v46, v1, v2, v8
	v_cvt_pk_bf16_f32 v50, v46, v47
	global_store_short v5, v50, s[10:11]
	global_store_short_d16_hi v5, v50, s[10:11] offset:128
	v_fma_f32 v8, -v0, v47, v22
	v_fma_f32 v9, v1, v47, v23
	v_fma_f32 v3, v0, v46, v9
	v_fma_f32 v2, v1, v46, v8
	v_cvt_pk_bf16_f32 v44, v2, v3
	global_store_short v5, v44, s[8:9] offset:1536
	global_store_short_d16_hi v5, v44, s[8:9] offset:1664
	v_fma_f32 v8, -v0, v3, v24
	v_fma_f32 v9, v1, v3, v25
	v_fma_f32 v47, v0, v2, v9
	v_fma_f32 v46, v1, v2, v8
	v_cvt_pk_bf16_f32 v50, v46, v47
	global_store_short v5, v50, s[8:9]
	global_store_short_d16_hi v5, v50, s[8:9] offset:128
	v_fma_f32 v8, -v0, v47, v26
	v_fma_f32 v9, v1, v47, v27
	v_fma_f32 v3, v0, v46, v9
	v_fma_f32 v2, v1, v46, v8
	s_add_u32 s8, s8, 0xffffe800
	s_addc_u32 s9, s9, -1
	s_add_u32 s10, s10, 0xffffe800
	s_addc_u32 s11, s11, -1
	global_load_dword v20, v4, s[4:5] offset:3072
	global_load_dword v21, v4, s[4:5] offset:3328
	global_load_dword v22, v4, s[4:5] offset:2048
	global_load_dword v23, v4, s[4:5] offset:2304
	global_load_dword v24, v4, s[4:5] offset:1024
	global_load_dword v25, v4, s[4:5] offset:1280
	global_load_dword v26, v4, s[4:5]
	global_load_dword v27, v4, s[4:5] offset:256
	s_add_u32 s4, s4, 0xfffff000
	s_addc_u32 s5, s5, -1
	s_waitcnt vmcnt(48)
	v_cvt_pk_bf16_f32 v44, v2, v3
	global_store_short v5, v44, s[10:11] offset:1536
	global_store_short_d16_hi v5, v44, s[10:11] offset:1664
	v_fma_f32 v8, -v0, v3, v28
	v_fma_f32 v9, v1, v3, v29
	v_fma_f32 v47, v0, v2, v9
	v_fma_f32 v46, v1, v2, v8
	v_cvt_pk_bf16_f32 v50, v46, v47
	global_store_short v5, v50, s[10:11]
	global_store_short_d16_hi v5, v50, s[10:11] offset:128
	v_fma_f32 v8, -v0, v47, v30
	v_fma_f32 v9, v1, v47, v31
	v_fma_f32 v3, v0, v46, v9
	v_fma_f32 v2, v1, v46, v8
	v_cvt_pk_bf16_f32 v44, v2, v3
	global_store_short v5, v44, s[8:9] offset:1536
	global_store_short_d16_hi v5, v44, s[8:9] offset:1664
	v_fma_f32 v8, -v0, v3, v32
	v_fma_f32 v9, v1, v3, v33
	v_fma_f32 v47, v0, v2, v9
	v_fma_f32 v46, v1, v2, v8
	v_cvt_pk_bf16_f32 v50, v46, v47
	global_store_short v5, v50, s[8:9]
	global_store_short_d16_hi v5, v50, s[8:9] offset:128
	v_fma_f32 v8, -v0, v47, v34
	v_fma_f32 v9, v1, v47, v35
	v_fma_f32 v3, v0, v46, v9
	v_fma_f32 v2, v1, v46, v8
	s_add_u32 s8, s8, 0xffffe800
	s_addc_u32 s9, s9, -1
	s_add_u32 s10, s10, 0xffffe800
	s_addc_u32 s11, s11, -1
	global_load_dword v28, v4, s[4:5] offset:3072
	global_load_dword v29, v4, s[4:5] offset:3328
	global_load_dword v30, v4, s[4:5] offset:2048
	global_load_dword v31, v4, s[4:5] offset:2304
	global_load_dword v32, v4, s[4:5] offset:1024
	global_load_dword v33, v4, s[4:5] offset:1280
	global_load_dword v34, v4, s[4:5]
	global_load_dword v35, v4, s[4:5] offset:256
	s_add_u32 s4, s4, 0xfffff000
	s_addc_u32 s5, s5, -1
	s_waitcnt vmcnt(48)
	v_cvt_pk_bf16_f32 v44, v2, v3
	global_store_short v5, v44, s[10:11] offset:1536
	global_store_short_d16_hi v5, v44, s[10:11] offset:1664
	v_fma_f32 v8, -v0, v3, v36
	v_fma_f32 v9, v1, v3, v37
	v_fma_f32 v47, v0, v2, v9
	v_fma_f32 v46, v1, v2, v8
	v_cvt_pk_bf16_f32 v50, v46, v47
	global_store_short v5, v50, s[10:11]
	global_store_short_d16_hi v5, v50, s[10:11] offset:128
	v_fma_f32 v8, -v0, v47, v38
	v_fma_f32 v9, v1, v47, v39
	v_fma_f32 v3, v0, v46, v9
	v_fma_f32 v2, v1, v46, v8
	v_cvt_pk_bf16_f32 v44, v2, v3
	global_store_short v5, v44, s[8:9] offset:1536
	global_store_short_d16_hi v5, v44, s[8:9] offset:1664
	v_fma_f32 v8, -v0, v3, v40
	v_fma_f32 v9, v1, v3, v41
	v_fma_f32 v47, v0, v2, v9
	v_fma_f32 v46, v1, v2, v8
	v_cvt_pk_bf16_f32 v50, v46, v47
	global_store_short v5, v50, s[8:9]
	global_store_short_d16_hi v5, v50, s[8:9] offset:128
	v_fma_f32 v8, -v0, v47, v42
	v_fma_f32 v9, v1, v47, v43
	v_fma_f32 v3, v0, v46, v9
	v_fma_f32 v2, v1, v46, v8
	s_add_u32 s8, s8, 0xffffe800
	s_addc_u32 s9, s9, -1
	s_add_u32 s10, s10, 0xffffe800
	s_addc_u32 s11, s11, -1
	s_sub_u32 s12, s12, 1
	s_cmp_lg_u32 s12, 0
	s_cbranch_scc1 .Lmy_s5b_d1
	s_branch .Lmy_after_s5
